# bf16 epilogue stores (in-proj, w_q, P.V outputs) marked non-temporal
# baseline (speedup 1.0000x reference)
.LBB0_789:
	s_lshl_b32 s9, s70, 8
	s_and_b32 s43, s9, 0x300
	s_lshl_b32 s42, s42, 5
	s_and_b64 s[6:7], s[80:81], exec
	s_cselect_b32 s6, s9, s43
	s_add_i32 s42, s42, s6
	s_ashr_i32 s65, s70, 2
	v_ashrrev_i32_e32 v173, 5, v182
	v_lshl_add_u32 v174, v174, 3, s42
	v_cmp_eq_u32_e32 vcc, s65, v173
	v_ashrrev_i32_e32 v175, 31, v174
	v_and_b32_e32 v246, 3, v243
	v_lshl_add_u32 v246, v246, 3, s42
	v_ashrrev_i32_e32 v247, 31, v246
	s_or_b64 s[52:53], s[80:81], vcc
	s_mov_b64 s[42:43], 0
	s_waitcnt vmcnt(0)
	s_and_saveexec_b64 s[6:7], s[52:53]
	s_cbranch_execz .LBB0_795
	v_mov_b32_e32 v184, v161
	v_mov_b32_e32 v185, v162
	v_mov_b32_e32 v161, v163
	v_pk_add_f32 v[160:161], v[184:185], v[160:161]
	v_mad_i64_i32 v[162:163], s[42:43], s26, v244, 0
	v_add_f32_e32 v160, v160, v161
	v_fmamk_f32 v160, v160, 0x3a800000, v241
	v_rsq_f32_e32 v160, v160
	v_lshl_add_u64 v[162:163], v[162:163], 1, s[34:35]
	v_lshl_add_u64 v[162:163], v[246:247], 1, v[162:163]
	s_and_b64 s[42:43], s[80:81], exec
	v_cndmask_b32_e64 v160, v160, 1.0, s[44:45]
	v_mul_f32_e32 v160, s38, v160
	v_pk_mul_f32 v[130:131], v[130:131], v[160:161] op_sel_hi:[1,0]
	v_pk_mul_f32 v[128:129], v[128:129], v[160:161] op_sel_hi:[1,0]
	v_pk_mul_f32 v[184:185], v[126:127], v[160:161] op_sel_hi:[1,0]
	v_pk_mul_f32 v[126:127], v[124:125], v[160:161] op_sel_hi:[1,0]
	v_cvt_pk_bf16_f32 v124, v128, v129
	v_cvt_pk_bf16_f32 v125, v130, v131
	v_pk_mul_f32 v[122:123], v[122:123], v[160:161] op_sel_hi:[1,0]
	v_cvt_pk_bf16_f32 v126, v126, v127
	v_cvt_pk_bf16_f32 v127, v184, v185
	ds_bpermute_b32 v226, v242, v124
	ds_bpermute_b32 v227, v242, v125
	ds_bpermute_b32 v228, v242, v126
	ds_bpermute_b32 v229, v242, v127
	v_pk_mul_f32 v[120:121], v[120:121], v[160:161] op_sel_hi:[1,0]
	s_nop 0
	v_pk_mul_f32 v[124:125], v[118:119], v[160:161] op_sel_hi:[1,0]
	v_pk_mul_f32 v[118:119], v[116:117], v[160:161] op_sel_hi:[1,0]
	v_cvt_pk_bf16_f32 v116, v120, v121
	v_cvt_pk_bf16_f32 v117, v122, v123
	s_nop 0
	v_cvt_pk_bf16_f32 v118, v118, v119
	v_cvt_pk_bf16_f32 v119, v124, v125
	ds_bpermute_b32 v230, v242, v116
	ds_bpermute_b32 v231, v242, v117
	ds_bpermute_b32 v232, v242, v118
	ds_bpermute_b32 v233, v242, v119
	s_waitcnt lgkmcnt(0)
	global_store_dwordx4 v[162:163], v[226:229], off nt
	global_store_dwordx4 v[162:163], v[230:233], off offset:256 nt
	s_or_b64 exec, exec, s[6:7]
	s_xor_b64 s[52:53], s[42:43], -1
	s_and_saveexec_b64 s[6:7], s[52:53]
	s_cbranch_execnz .LBB0_796

.LBB0_792:
	v_add_f32_e32 v117, v156, v157
	v_add_f32_e32 v118, v158, v159
	v_add_f32_e32 v117, v117, v118
	v_fmamk_f32 v117, v117, 0x3a800000, v241
	v_rsq_f32_e32 v118, v117
	v_add_u32_e32 v116, 16, v244
	v_mad_i64_i32 v[116:117], s[42:43], s26, v116, 0
	v_cndmask_b32_e64 v118, v118, 1.0, s[44:45]
	v_lshl_add_u64 v[116:117], v[116:117], 1, s[34:35]
	v_mul_f32_e32 v118, s38, v118
	v_lshl_add_u64 v[116:117], v[246:247], 1, v[116:117]
	v_pk_mul_f32 v[114:115], v[114:115], v[118:119] op_sel_hi:[1,0]
	v_pk_mul_f32 v[112:113], v[112:113], v[118:119] op_sel_hi:[1,0]
	v_pk_mul_f32 v[120:121], v[110:111], v[118:119] op_sel_hi:[1,0]
	v_pk_mul_f32 v[110:111], v[108:109], v[118:119] op_sel_hi:[1,0]
	v_cvt_pk_bf16_f32 v108, v112, v113
	v_cvt_pk_bf16_f32 v109, v114, v115
	s_and_b64 s[52:53], s[80:81], exec
	v_cvt_pk_bf16_f32 v110, v110, v111
	v_cvt_pk_bf16_f32 v111, v120, v121
	ds_bpermute_b32 v226, v242, v108
	ds_bpermute_b32 v227, v242, v109
	ds_bpermute_b32 v228, v242, v110
	ds_bpermute_b32 v229, v242, v111
	v_pk_mul_f32 v[106:107], v[106:107], v[118:119] op_sel_hi:[1,0]
	v_pk_mul_f32 v[104:105], v[104:105], v[118:119] op_sel_hi:[1,0]
	v_pk_mul_f32 v[108:109], v[102:103], v[118:119] op_sel_hi:[1,0]
	v_pk_mul_f32 v[102:103], v[100:101], v[118:119] op_sel_hi:[1,0]
	v_cvt_pk_bf16_f32 v100, v104, v105
	v_cvt_pk_bf16_f32 v101, v106, v107
	s_nop 0
	v_cvt_pk_bf16_f32 v102, v102, v103
	v_cvt_pk_bf16_f32 v103, v108, v109
	ds_bpermute_b32 v230, v242, v100
	ds_bpermute_b32 v231, v242, v101
	ds_bpermute_b32 v232, v242, v102
	ds_bpermute_b32 v233, v242, v103
	s_waitcnt lgkmcnt(0)
	global_store_dwordx4 v[116:117], v[226:229], off nt
	global_store_dwordx4 v[116:117], v[230:233], off offset:256 nt
	s_or_b64 exec, exec, s[6:7]
	s_xor_b64 s[42:43], s[52:53], -1
	s_and_saveexec_b64 s[6:7], s[42:43]
	s_cbranch_execnz .LBB0_798

.LBB0_794:
	v_add_f32_e32 v101, v152, v153
	v_add_f32_e32 v102, v154, v155
	v_add_f32_e32 v101, v101, v102
	v_fmamk_f32 v101, v101, 0x3a800000, v241
	v_rsq_f32_e32 v102, v101
	v_add_u32_e32 v100, 32, v244
	v_mad_i64_i32 v[100:101], s[42:43], s26, v100, 0
	v_cndmask_b32_e64 v102, v102, 1.0, s[44:45]
	v_lshl_add_u64 v[100:101], v[100:101], 1, s[34:35]
	v_mul_f32_e32 v102, s38, v102
	v_lshl_add_u64 v[100:101], v[246:247], 1, v[100:101]
	v_pk_mul_f32 v[98:99], v[98:99], v[102:103] op_sel_hi:[1,0]
	v_pk_mul_f32 v[96:97], v[96:97], v[102:103] op_sel_hi:[1,0]
	v_pk_mul_f32 v[104:105], v[94:95], v[102:103] op_sel_hi:[1,0]
	v_pk_mul_f32 v[94:95], v[92:93], v[102:103] op_sel_hi:[1,0]
	v_cvt_pk_bf16_f32 v92, v96, v97
	v_cvt_pk_bf16_f32 v93, v98, v99
	s_and_b64 s[70:71], s[80:81], exec
	v_cvt_pk_bf16_f32 v94, v94, v95
	v_cvt_pk_bf16_f32 v95, v104, v105
	ds_bpermute_b32 v226, v242, v92
	ds_bpermute_b32 v227, v242, v93
	ds_bpermute_b32 v228, v242, v94
	ds_bpermute_b32 v229, v242, v95
	v_pk_mul_f32 v[90:91], v[90:91], v[102:103] op_sel_hi:[1,0]
	v_pk_mul_f32 v[88:89], v[88:89], v[102:103] op_sel_hi:[1,0]
	v_pk_mul_f32 v[92:93], v[86:87], v[102:103] op_sel_hi:[1,0]
	v_pk_mul_f32 v[86:87], v[84:85], v[102:103] op_sel_hi:[1,0]
	v_cvt_pk_bf16_f32 v84, v88, v89
	v_cvt_pk_bf16_f32 v85, v90, v91
	s_nop 0
	v_cvt_pk_bf16_f32 v86, v86, v87
	v_cvt_pk_bf16_f32 v87, v92, v93
	ds_bpermute_b32 v230, v242, v84
	ds_bpermute_b32 v231, v242, v85
	ds_bpermute_b32 v232, v242, v86
	ds_bpermute_b32 v233, v242, v87
	s_waitcnt lgkmcnt(0)
	global_store_dwordx4 v[100:101], v[226:229], off nt
	global_store_dwordx4 v[100:101], v[230:233], off offset:256 nt
	s_or_b64 exec, exec, s[6:7]
	s_xor_b64 s[42:43], s[70:71], -1
	s_and_saveexec_b64 s[6:7], s[42:43]
	s_cbranch_execnz .LBB0_800
	s_branch .LBB0_801

.LBB0_801:
	s_or_b64 exec, exec, s[6:7]
	s_mov_b64 s[6:7], 0
	s_mov_b64 s[52:53], 0
	s_and_saveexec_b64 s[42:43], s[70:71]
	s_cbranch_execz .LBB0_803
	v_add_f32_e32 v85, v148, v149
	v_add_f32_e32 v86, v150, v151
	v_add_f32_e32 v85, v85, v86
	v_fmamk_f32 v85, v85, 0x3a800000, v241
	v_rsq_f32_e32 v86, v85
	v_add_u32_e32 v84, 48, v244
	v_mad_i64_i32 v[84:85], s[52:53], s26, v84, 0
	v_cndmask_b32_e64 v86, v86, 1.0, s[44:45]
	v_lshl_add_u64 v[84:85], v[84:85], 1, s[34:35]
	v_mul_f32_e32 v86, s38, v86
	v_lshl_add_u64 v[84:85], v[246:247], 1, v[84:85]
	v_pk_mul_f32 v[82:83], v[82:83], v[86:87] op_sel_hi:[1,0]
	v_pk_mul_f32 v[80:81], v[80:81], v[86:87] op_sel_hi:[1,0]
	v_pk_mul_f32 v[88:89], v[78:79], v[86:87] op_sel_hi:[1,0]
	v_pk_mul_f32 v[78:79], v[76:77], v[86:87] op_sel_hi:[1,0]
	v_cvt_pk_bf16_f32 v76, v80, v81
	v_cvt_pk_bf16_f32 v77, v82, v83
	s_and_b64 s[52:53], s[80:81], exec
	v_cvt_pk_bf16_f32 v78, v78, v79
	v_cvt_pk_bf16_f32 v79, v88, v89
	ds_bpermute_b32 v226, v242, v76
	ds_bpermute_b32 v227, v242, v77
	ds_bpermute_b32 v228, v242, v78
	ds_bpermute_b32 v229, v242, v79
	v_pk_mul_f32 v[74:75], v[74:75], v[86:87] op_sel_hi:[1,0]
	v_pk_mul_f32 v[72:73], v[72:73], v[86:87] op_sel_hi:[1,0]
	v_pk_mul_f32 v[76:77], v[70:71], v[86:87] op_sel_hi:[1,0]
	v_pk_mul_f32 v[70:71], v[68:69], v[86:87] op_sel_hi:[1,0]
	v_cvt_pk_bf16_f32 v68, v72, v73
	v_cvt_pk_bf16_f32 v69, v74, v75
	s_nop 0
	v_cvt_pk_bf16_f32 v70, v70, v71
	v_cvt_pk_bf16_f32 v71, v76, v77
	ds_bpermute_b32 v230, v242, v68
	ds_bpermute_b32 v231, v242, v69
	ds_bpermute_b32 v232, v242, v70
	ds_bpermute_b32 v233, v242, v71
	s_waitcnt lgkmcnt(0)
	global_store_dwordx4 v[84:85], v[226:229], off nt
	global_store_dwordx4 v[84:85], v[230:233], off offset:256 nt
.LBB0_803:
	s_or_b64 exec, exec, s[42:43]
	s_nop 0
	v_add_u32_e32 v68, 0x80, v182
	v_ashrrev_i32_e32 v68, 5, v68
	v_cmp_eq_u32_e32 vcc, s65, v68
	s_or_b64 s[52:53], s[52:53], vcc
	s_and_saveexec_b64 s[42:43], s[52:53]
	s_cbranch_execz .LBB0_814
	v_mov_b32_e32 v68, v145
	v_mov_b32_e32 v69, v146
	v_mov_b32_e32 v145, v147
	v_pk_add_f32 v[68:69], v[68:69], v[144:145]
	v_mad_i64_i32 v[70:71], s[6:7], s26, v245, 0
	v_add_f32_e32 v68, v68, v69
	v_fmamk_f32 v68, v68, 0x3a800000, v241
	v_rsq_f32_e32 v68, v68
	v_lshl_add_u64 v[70:71], v[70:71], 1, s[34:35]
	v_lshl_add_u64 v[70:71], v[246:247], 1, v[70:71]
	s_and_b64 s[6:7], s[80:81], exec
	v_cndmask_b32_e64 v68, v68, 1.0, s[44:45]
	v_mul_f32_e32 v68, s38, v68
	v_pk_mul_f32 v[66:67], v[66:67], v[68:69] op_sel_hi:[1,0]
	v_pk_mul_f32 v[64:65], v[64:65], v[68:69] op_sel_hi:[1,0]
	v_pk_mul_f32 v[72:73], v[62:63], v[68:69] op_sel_hi:[1,0]
	v_pk_mul_f32 v[62:63], v[60:61], v[68:69] op_sel_hi:[1,0]
	v_cvt_pk_bf16_f32 v60, v64, v65
	v_cvt_pk_bf16_f32 v61, v66, v67
	v_pk_mul_f32 v[58:59], v[58:59], v[68:69] op_sel_hi:[1,0]
	v_cvt_pk_bf16_f32 v62, v62, v63
	v_cvt_pk_bf16_f32 v63, v72, v73
	ds_bpermute_b32 v226, v242, v60
	ds_bpermute_b32 v227, v242, v61
	ds_bpermute_b32 v228, v242, v62
	ds_bpermute_b32 v229, v242, v63
	v_pk_mul_f32 v[56:57], v[56:57], v[68:69] op_sel_hi:[1,0]
	s_nop 0
	v_pk_mul_f32 v[60:61], v[54:55], v[68:69] op_sel_hi:[1,0]
	v_pk_mul_f32 v[54:55], v[52:53], v[68:69] op_sel_hi:[1,0]
	v_cvt_pk_bf16_f32 v52, v56, v57
	v_cvt_pk_bf16_f32 v53, v58, v59
	s_nop 0
	v_cvt_pk_bf16_f32 v54, v54, v55
	v_cvt_pk_bf16_f32 v55, v60, v61
	ds_bpermute_b32 v230, v242, v52
	ds_bpermute_b32 v231, v242, v53
	ds_bpermute_b32 v232, v242, v54
	ds_bpermute_b32 v233, v242, v55
	s_waitcnt lgkmcnt(0)
	global_store_dwordx4 v[70:71], v[226:229], off nt
	global_store_dwordx4 v[70:71], v[230:233], off offset:256 nt
	s_or_b64 exec, exec, s[42:43]
	s_xor_b64 s[52:53], s[6:7], -1
	s_and_saveexec_b64 s[42:43], s[52:53]
	s_cbranch_execnz .LBB0_815

.LBB0_806:
	v_add_f32_e32 v53, v140, v141
	v_add_f32_e32 v54, v142, v143
	v_add_f32_e32 v53, v53, v54
	v_fmamk_f32 v53, v53, 0x3a800000, v241
	v_rsq_f32_e32 v54, v53
	v_add_u32_e32 v52, 0x90, v244
	v_mad_i64_i32 v[52:53], s[6:7], s26, v52, 0
	v_cndmask_b32_e64 v54, v54, 1.0, s[44:45]
	v_lshl_add_u64 v[52:53], v[52:53], 1, s[34:35]
	v_mul_f32_e32 v54, s38, v54
	v_lshl_add_u64 v[52:53], v[246:247], 1, v[52:53]
	v_pk_mul_f32 v[50:51], v[50:51], v[54:55] op_sel_hi:[1,0]
	v_pk_mul_f32 v[48:49], v[48:49], v[54:55] op_sel_hi:[1,0]
	v_pk_mul_f32 v[56:57], v[46:47], v[54:55] op_sel_hi:[1,0]
	v_pk_mul_f32 v[46:47], v[44:45], v[54:55] op_sel_hi:[1,0]
	v_cvt_pk_bf16_f32 v44, v48, v49
	v_cvt_pk_bf16_f32 v45, v50, v51
	s_and_b64 s[52:53], s[80:81], exec
	v_cvt_pk_bf16_f32 v46, v46, v47
	v_cvt_pk_bf16_f32 v47, v56, v57
	ds_bpermute_b32 v226, v242, v44
	ds_bpermute_b32 v227, v242, v45
	ds_bpermute_b32 v228, v242, v46
	ds_bpermute_b32 v229, v242, v47
	v_pk_mul_f32 v[42:43], v[42:43], v[54:55] op_sel_hi:[1,0]
	v_pk_mul_f32 v[40:41], v[40:41], v[54:55] op_sel_hi:[1,0]
	v_pk_mul_f32 v[44:45], v[38:39], v[54:55] op_sel_hi:[1,0]
	v_pk_mul_f32 v[38:39], v[36:37], v[54:55] op_sel_hi:[1,0]
	v_cvt_pk_bf16_f32 v36, v40, v41
	v_cvt_pk_bf16_f32 v37, v42, v43
	s_nop 0
	v_cvt_pk_bf16_f32 v38, v38, v39
	v_cvt_pk_bf16_f32 v39, v44, v45
	ds_bpermute_b32 v230, v242, v36
	ds_bpermute_b32 v231, v242, v37
	ds_bpermute_b32 v232, v242, v38
	ds_bpermute_b32 v233, v242, v39
	s_waitcnt lgkmcnt(0)
	global_store_dwordx4 v[52:53], v[226:229], off nt
	global_store_dwordx4 v[52:53], v[230:233], off offset:256 nt
	s_or_b64 exec, exec, s[42:43]
	s_xor_b64 s[42:43], s[52:53], -1
	s_and_saveexec_b64 s[6:7], s[42:43]
	s_cbranch_execnz .LBB0_817

.LBB0_808:
	v_add_f32_e32 v37, v136, v137
	v_add_f32_e32 v38, v138, v139
	v_add_f32_e32 v37, v37, v38
	v_fmamk_f32 v37, v37, 0x3a800000, v241
	v_rsq_f32_e32 v38, v37
	v_add_u32_e32 v36, 0xa0, v244
	v_mad_i64_i32 v[36:37], s[42:43], s26, v36, 0
	v_cndmask_b32_e64 v38, v38, 1.0, s[44:45]
	v_lshl_add_u64 v[36:37], v[36:37], 1, s[34:35]
	v_mul_f32_e32 v38, s38, v38
	v_lshl_add_u64 v[36:37], v[246:247], 1, v[36:37]
	v_pk_mul_f32 v[34:35], v[34:35], v[38:39] op_sel_hi:[1,0]
	v_pk_mul_f32 v[32:33], v[32:33], v[38:39] op_sel_hi:[1,0]
	v_pk_mul_f32 v[40:41], v[30:31], v[38:39] op_sel_hi:[1,0]
	v_pk_mul_f32 v[30:31], v[28:29], v[38:39] op_sel_hi:[1,0]
	v_cvt_pk_bf16_f32 v28, v32, v33
	v_cvt_pk_bf16_f32 v29, v34, v35
	s_and_b64 s[42:43], s[80:81], exec
	v_cvt_pk_bf16_f32 v30, v30, v31
	v_cvt_pk_bf16_f32 v31, v40, v41
	ds_bpermute_b32 v226, v242, v28
	ds_bpermute_b32 v227, v242, v29
	ds_bpermute_b32 v228, v242, v30
	ds_bpermute_b32 v229, v242, v31
	v_pk_mul_f32 v[26:27], v[26:27], v[38:39] op_sel_hi:[1,0]
	v_pk_mul_f32 v[24:25], v[24:25], v[38:39] op_sel_hi:[1,0]
	v_pk_mul_f32 v[28:29], v[22:23], v[38:39] op_sel_hi:[1,0]
	v_pk_mul_f32 v[22:23], v[20:21], v[38:39] op_sel_hi:[1,0]
	v_cvt_pk_bf16_f32 v20, v24, v25
	v_cvt_pk_bf16_f32 v21, v26, v27
	s_nop 0
	v_cvt_pk_bf16_f32 v22, v22, v23
	v_cvt_pk_bf16_f32 v23, v28, v29
	ds_bpermute_b32 v230, v242, v20
	ds_bpermute_b32 v231, v242, v21
	ds_bpermute_b32 v232, v242, v22
	ds_bpermute_b32 v233, v242, v23
	s_waitcnt lgkmcnt(0)
	global_store_dwordx4 v[36:37], v[226:229], off nt
	global_store_dwordx4 v[36:37], v[230:233], off offset:256 nt
.LBB0_809:
	s_or_b64 exec, exec, s[6:7]
	s_nop 0
	v_add_u32_e32 v20, 0xb0, v182
	v_ashrrev_i32_e32 v20, 5, v20
	v_cmp_eq_u32_e32 vcc, s65, v20
	s_or_b64 s[42:43], s[42:43], vcc
	s_and_saveexec_b64 s[6:7], s[42:43]
	s_cbranch_execz .LBB0_811
	v_add_f32_e32 v21, v132, v133
	v_add_f32_e32 v22, v134, v135
	v_add_f32_e32 v21, v21, v22
	v_fmamk_f32 v21, v21, 0x3a800000, v241
	v_rsq_f32_e32 v22, v21
	v_add_u32_e32 v20, 0xb0, v244
	v_mad_i64_i32 v[20:21], s[42:43], s26, v20, 0
	v_cndmask_b32_e64 v22, v22, 1.0, s[44:45]
	v_lshl_add_u64 v[20:21], v[20:21], 1, s[34:35]
	v_mul_f32_e32 v22, s38, v22
	v_lshl_add_u64 v[20:21], v[246:247], 1, v[20:21]
	v_pk_mul_f32 v[18:19], v[18:19], v[22:23] op_sel_hi:[1,0]
	v_pk_mul_f32 v[16:17], v[16:17], v[22:23] op_sel_hi:[1,0]
	v_pk_mul_f32 v[24:25], v[14:15], v[22:23] op_sel_hi:[1,0]
	v_pk_mul_f32 v[14:15], v[12:13], v[22:23] op_sel_hi:[1,0]
	v_cvt_pk_bf16_f32 v12, v16, v17
	v_cvt_pk_bf16_f32 v13, v18, v19
	v_pk_mul_f32 v[10:11], v[10:11], v[22:23] op_sel_hi:[1,0]
	v_cvt_pk_bf16_f32 v14, v14, v15
	v_cvt_pk_bf16_f32 v15, v24, v25
	ds_bpermute_b32 v226, v242, v12
	ds_bpermute_b32 v227, v242, v13
	ds_bpermute_b32 v228, v242, v14
	ds_bpermute_b32 v229, v242, v15
	v_pk_mul_f32 v[8:9], v[8:9], v[22:23] op_sel_hi:[1,0]
	s_nop 0
	v_pk_mul_f32 v[12:13], v[6:7], v[22:23] op_sel_hi:[1,0]
	v_pk_mul_f32 v[6:7], v[4:5], v[22:23] op_sel_hi:[1,0]
	v_cvt_pk_bf16_f32 v4, v8, v9
	v_cvt_pk_bf16_f32 v5, v10, v11
	s_nop 0
	v_cvt_pk_bf16_f32 v6, v6, v7
	v_cvt_pk_bf16_f32 v7, v12, v13
	ds_bpermute_b32 v230, v242, v4
	ds_bpermute_b32 v231, v242, v5
	ds_bpermute_b32 v232, v242, v6
	ds_bpermute_b32 v233, v242, v7
	s_waitcnt lgkmcnt(0)
	global_store_dwordx4 v[20:21], v[226:229], off nt
	global_store_dwordx4 v[20:21], v[230:233], off offset:256 nt
